# v044 with SSD waves at higher issue priority (2/3) than LRU waves (0/1)
# speedup vs baseline: 1.0007x; 1.0007x over previous
.LBB0_572:
	v_mov_b32_e32 v152, v182
	s_nop 0
	v_readlane_b32 s32, v165, 31
	s_nop 3
	v_sub_f32_e32 v248, s32, v165
	v_exp_f32_e32 v249, v165
	v_exp_f32_e32 v248, v248
	v_cmp_gt_u32_e32 vcc, 32, v152
	s_and_saveexec_b64 s[6:7], vcc
	v_lshl_add_u32 v64, v152, 3, s49
	ds_write_b64 v64, v[164:165]
	v_lshl_add_u32 v250, v152, 2, s49
	ds_write_b32 v250, v248 offset:1024
	ds_write_b32 v250, v249 offset:1152
	s_or_b64 exec, exec, s[6:7]
	s_bitcmp1_b32 s34, 0
	s_cselect_b32 s6, 0xe000, 0
	s_add_i32 s42, s6, 0
	v_and_b32_e32 v197, 31, v152
	v_ashrrev_i32_e32 v196, 5, v152
	s_add_i32 s34, s42, s39
	s_waitcnt lgkmcnt(0)
	v_lshlrev_b32_e32 v65, 8, v196
	v_lshlrev_b32_e32 v66, 1, v197
	v_and_b32_e32 v164, 0xffffffe0, v152
	s_waitcnt lgkmcnt(0)
	v_add3_u32 v195, s34, v65, v66
	v_add_u32_e32 v90, s49, v164
	v_mov_b32_e32 v64, s49
	ds_read_b128 v[124:127], v90
	ds_read_b128 v[120:123], v90 offset:16
	ds_read_b32 v198, v64 offset:252
	ds_read_u16 v66, v195 offset:32768
	ds_read_u16 v67, v195 offset:32832
	ds_read_u16 v70, v195 offset:32896
	ds_read_u16 v71, v195 offset:32960
	ds_read_u16 v74, v195 offset:33280
	ds_read_u16 v75, v195 offset:33344
	ds_read_u16 v78, v195 offset:33408
	ds_read_u16 v94, v195 offset:34496
	ds_read_b128 v[132:135], v90 offset:64
	ds_read_b128 v[128:131], v90 offset:80
	ds_read_b128 v[112:115], v90 offset:128
	ds_read_u16 v79, v195 offset:33472
	ds_read_u16 v82, v195 offset:33792
	ds_read_u16 v83, v195 offset:33856
	ds_read_u16 v86, v195 offset:33920
	ds_read_u16 v87, v195 offset:33984
	ds_read_u16 v91, v195 offset:34304
	ds_read_u16 v92, v195 offset:34368
	ds_read_u16 v95, v195 offset:34432
	ds_read_b128 v[116:119], v90 offset:144
	ds_read_b128 v[104:107], v90 offset:192
	ds_read_b128 v[100:103], v90 offset:208
	v_lshrrev_b32_e32 v250, 1, v164
	v_add_u32_e32 v250, s49, v250
	ds_read_b128 v[216:219], v250 offset:1024
	ds_read_b128 v[220:223], v250 offset:1056
	ds_read_b128 v[224:227], v250 offset:1088
	ds_read_b128 v[228:231], v250 offset:1120
	ds_read_b128 v[232:235], v250 offset:1152
	ds_read_b128 v[236:239], v250 offset:1184
	ds_read_b128 v[240:243], v250 offset:1216
	ds_read_b128 v[244:247], v250 offset:1248
	s_waitcnt lgkmcnt(0)
	v_lshlrev_b32_e32 v169, 16, v92
	v_lshlrev_b32_e32 v181, 16, v67
	v_lshlrev_b32_e32 v180, 16, v66
	v_mov_b32_e32 v66, v124
	v_mov_b32_e32 v67, v126
	v_lshlrev_b32_e32 v179, 16, v71
	v_lshlrev_b32_e32 v178, 16, v70
	v_mov_b32_e32 v70, v120
	v_mov_b32_e32 v71, v122
	v_lshlrev_b32_e32 v177, 16, v75
	v_lshlrev_b32_e32 v176, 16, v74
	v_mov_b32_e32 v74, v132
	v_mov_b32_e32 v75, v134
	v_lshlrev_b32_e32 v175, 16, v79
	v_lshlrev_b32_e32 v174, 16, v78
	v_mov_b32_e32 v78, v128
	v_mov_b32_e32 v79, v130
	v_lshlrev_b32_e32 v173, 16, v83
	v_lshlrev_b32_e32 v172, 16, v82
	v_mov_b32_e32 v82, v112
	v_mov_b32_e32 v83, v114
	v_lshlrev_b32_e32 v171, 16, v87
	v_lshlrev_b32_e32 v170, 16, v86
	v_mov_b32_e32 v86, v116
	v_mov_b32_e32 v87, v118
	v_lshlrev_b32_e32 v168, 16, v91
	v_mov_b32_e32 v90, v104
	v_mov_b32_e32 v91, v106
	v_lshlrev_b32_e32 v167, 16, v94
	v_lshlrev_b32_e32 v166, 16, v95
	v_mov_b32_e32 v94, v100
	v_mov_b32_e32 v95, v102
	v_pk_mul_f32 v[66:67], v[66:67], v[180:181]
	v_pk_mul_f32 v[70:71], v[70:71], v[178:179]
	v_pk_mul_f32 v[74:75], v[74:75], v[176:177]
	v_pk_mul_f32 v[78:79], v[78:79], v[174:175]
	v_pk_mul_f32 v[82:83], v[82:83], v[172:173]
	v_pk_mul_f32 v[86:87], v[86:87], v[170:171]
	v_pk_mul_f32 v[90:91], v[90:91], v[168:169]
	v_pk_mul_f32 v[94:95], v[94:95], v[166:167]
	v_pk_mul_f32 v[64:65], v[66:67], v[216:217]
	v_pk_mul_f32 v[68:69], v[70:71], v[218:219]
	v_pk_mul_f32 v[72:73], v[74:75], v[220:221]
	v_pk_mul_f32 v[76:77], v[78:79], v[222:223]
	v_pk_mul_f32 v[80:81], v[82:83], v[224:225]
	v_pk_mul_f32 v[84:85], v[86:87], v[226:227]
	v_pk_mul_f32 v[88:89], v[90:91], v[228:229]
	v_pk_mul_f32 v[92:93], v[94:95], v[230:231]
	v_cvt_pk_bf16_f32 v148, v66, v67
	v_cvt_pk_bf16_f32 v149, v70, v71
	v_cvt_pk_bf16_f32 v150, v74, v75
	v_cvt_pk_bf16_f32 v151, v78, v79
	v_cvt_pk_bf16_f32 v108, v64, v65
	v_cvt_pk_bf16_f32 v109, v68, v69
	v_cvt_pk_bf16_f32 v110, v72, v73
	v_cvt_pk_bf16_f32 v111, v76, v77
	v_cvt_pk_bf16_f32 v140, v82, v83
	v_cvt_pk_bf16_f32 v141, v86, v87
	v_cvt_pk_bf16_f32 v142, v90, v91
	v_cvt_pk_bf16_f32 v143, v94, v95
	v_cvt_pk_bf16_f32 v96, v80, v81
	v_cvt_pk_bf16_f32 v97, v84, v85
	v_cvt_pk_bf16_f32 v98, v88, v89
	v_cvt_pk_bf16_f32 v99, v92, v93
	s_setprio 3
	v_bitop3_b32 v64, v196, v152, 15 bitop3:0x78
	v_lshlrev_b32_e32 v100, 8, v197
	v_lshlrev_b32_e32 v64, 4, v64
	v_add3_u32 v68, v64, v100, s42
	ds_read_b128 v[80:83], v68 offset:8192
	ds_read_b128 v[84:87], v68
	v_cvt_pk_bf16_f32 v64, v0, v1
	v_cvt_pk_bf16_f32 v65, v2, v3
	v_cvt_pk_bf16_f32 v66, v4, v5
	v_cvt_pk_bf16_f32 v67, v6, v7
	v_add_u32_e32 v104, 2, v196
	v_bitop3_b32 v102, v104, v152, 15 bitop3:0x78
	s_waitcnt lgkmcnt(0)
	v_mfma_f32_32x32x16_bf16 v[64:79], v[80:83], v[64:67], 0
	v_lshlrev_b32_e32 v102, 4, v102
	v_add3_u32 v102, v102, v100, s42
	ds_read_b128 v[136:139], v102 offset:8192
	ds_read_b128 v[144:147], v102
	v_add_u32_e32 v102, 4, v196
	v_bitop3_b32 v102, v102, v152, 15 bitop3:0x78
	v_lshlrev_b32_e32 v102, 4, v102
	v_cvt_pk_bf16_f32 v200, v8, v9
	v_mfma_f32_32x32x16_bf16 v[80:95], v[84:87], v[80:83], 0
	v_cvt_pk_bf16_f32 v201, v10, v11
	v_cvt_pk_bf16_f32 v202, v12, v13
	v_cvt_pk_bf16_f32 v203, v14, v15
	v_add3_u32 v102, v102, v100, s42
	v_cvt_pk_bf16_f32 v208, v48, v49
	v_cvt_pk_bf16_f32 v209, v50, v51
	v_cvt_pk_bf16_f32 v210, v52, v53
	s_waitcnt lgkmcnt(0)
	v_mfma_f32_32x32x16_bf16 v[80:95], v[144:147], v[136:139], v[80:95]
	v_cvt_pk_bf16_f32 v211, v54, v55
	v_mfma_f32_32x32x16_bf16 v[64:79], v[136:139], v[200:203], v[64:79]
	ds_read_b128 v[136:139], v102 offset:8192
	ds_read_b128 v[144:147], v102
	v_add_u32_e32 v102, 6, v196
	v_bitop3_b32 v102, v102, v152, 15 bitop3:0x78
	v_lshlrev_b32_e32 v102, 4, v102
	v_cvt_pk_bf16_f32 v200, v16, v17
	v_cvt_pk_bf16_f32 v201, v18, v19
	v_cvt_pk_bf16_f32 v202, v20, v21
	s_waitcnt lgkmcnt(0)
	v_mfma_f32_32x32x16_bf16 v[80:95], v[144:147], v[136:139], v[80:95]
	v_cvt_pk_bf16_f32 v203, v22, v23
	v_add3_u32 v102, v102, v100, s42
	s_nop 0
	v_mfma_f32_32x32x16_bf16 v[64:79], v[136:139], v[200:203], v[64:79]
	ds_read_b128 v[136:139], v102 offset:8192
	ds_read_b128 v[144:147], v102
	v_add_u32_e32 v102, 8, v196
	v_bitop3_b32 v102, v102, v152, 15 bitop3:0x78
	v_lshlrev_b32_e32 v102, 4, v102
	v_cvt_pk_bf16_f32 v200, v24, v25
	v_cvt_pk_bf16_f32 v201, v26, v27
	v_cvt_pk_bf16_f32 v202, v28, v29
	s_waitcnt lgkmcnt(0)
	v_mfma_f32_32x32x16_bf16 v[80:95], v[144:147], v[136:139], v[80:95]
	v_cvt_pk_bf16_f32 v203, v30, v31
	v_add3_u32 v102, v102, v100, s42
	s_nop 0
	v_mfma_f32_32x32x16_bf16 v[64:79], v[136:139], v[200:203], v[64:79]
	ds_read_b128 v[136:139], v102 offset:8192
	ds_read_b128 v[144:147], v102
	v_add_u32_e32 v102, 10, v196
	v_bitop3_b32 v102, v102, v152, 15 bitop3:0x78
	v_lshlrev_b32_e32 v102, 4, v102
	v_cvt_pk_bf16_f32 v200, v32, v33
	v_cvt_pk_bf16_f32 v201, v34, v35
	v_cvt_pk_bf16_f32 v202, v36, v37
	s_waitcnt lgkmcnt(0)
	v_mfma_f32_32x32x16_bf16 v[80:95], v[144:147], v[136:139], v[80:95]
	v_cvt_pk_bf16_f32 v203, v38, v39
	v_add3_u32 v102, v102, v100, s42
	s_nop 0
	v_mfma_f32_32x32x16_bf16 v[64:79], v[136:139], v[200:203], v[64:79]
	ds_read_b128 v[136:139], v102 offset:8192
	ds_read_b128 v[144:147], v102
	v_add_u32_e32 v102, 12, v196
	v_bitop3_b32 v102, v102, v152, 15 bitop3:0x78
	v_lshlrev_b32_e32 v102, 4, v102
	v_cvt_pk_bf16_f32 v200, v40, v41
	v_cvt_pk_bf16_f32 v201, v42, v43
	v_cvt_pk_bf16_f32 v202, v44, v45
	s_waitcnt lgkmcnt(0)
	v_mfma_f32_32x32x16_bf16 v[80:95], v[144:147], v[136:139], v[80:95]
	v_cvt_pk_bf16_f32 v203, v46, v47
	v_add3_u32 v102, v102, v100, s42
	v_cvt_pk_bf16_f32 v144, v56, v57
	v_cvt_pk_bf16_f32 v145, v58, v59
	v_cvt_pk_bf16_f32 v146, v60, v61
	v_cvt_pk_bf16_f32 v147, v62, v63
	v_mfma_f32_32x32x16_bf16 v[64:79], v[136:139], v[200:203], v[64:79]
	ds_read_b128 v[200:203], v102 offset:8192
	ds_read_b128 v[204:207], v102
	v_add_u32_e32 v102, 14, v196
	v_bitop3_b32 v102, v102, v152, 15 bitop3:0x78
	v_lshlrev_b32_e32 v102, 4, v102
	v_add3_u32 v100, v102, v100, s42
	ds_read_b128 v[136:139], v100 offset:8192
	ds_read_b128 v[212:215], v100
	s_waitcnt lgkmcnt(0)
	v_mfma_f32_32x32x16_bf16 v[80:95], v[204:207], v[200:203], v[80:95]
	v_mfma_f32_32x32x16_bf16 v[80:95], v[212:215], v[136:139], v[80:95]
	s_setprio 2
	v_mfma_f32_32x32x16_bf16 v[64:79], v[200:203], v[208:211], v[64:79]
	v_mfma_f32_32x32x16_bf16 v[64:79], v[136:139], v[144:147], v[64:79]
	v_sub_f32_e32 v216, v165, v125
	v_sub_f32_e32 v217, v165, v127
	v_sub_f32_e32 v218, v165, v121
	v_sub_f32_e32 v219, v165, v123
	v_sub_f32_e32 v220, v165, v133
	v_sub_f32_e32 v221, v165, v135
	v_sub_f32_e32 v222, v165, v129
	v_sub_f32_e32 v223, v165, v131
	v_sub_f32_e32 v224, v165, v113
	v_sub_f32_e32 v225, v165, v115
	v_sub_f32_e32 v226, v165, v117
	v_sub_f32_e32 v227, v165, v119
	v_sub_f32_e32 v228, v165, v105
	v_sub_f32_e32 v229, v165, v107
	v_sub_f32_e32 v230, v165, v101
	v_sub_f32_e32 v231, v165, v103
	v_exp_f32_e32 v216, v216
	v_exp_f32_e32 v217, v217
	v_exp_f32_e32 v218, v218
	v_exp_f32_e32 v219, v219
	v_exp_f32_e32 v220, v220
	v_exp_f32_e32 v221, v221
	v_exp_f32_e32 v222, v222
	v_exp_f32_e32 v223, v223
	v_exp_f32_e32 v224, v224
	v_exp_f32_e32 v225, v225
	v_exp_f32_e32 v226, v226
	v_exp_f32_e32 v227, v227
	v_exp_f32_e32 v228, v228
	v_exp_f32_e32 v229, v229
	v_exp_f32_e32 v230, v230
	v_exp_f32_e32 v231, v231
	v_mul_f32_e32 v216, v216, v80
	v_mul_f32_e32 v217, v217, v81
	v_mul_f32_e32 v218, v218, v82
	v_mul_f32_e32 v219, v219, v83
	v_mul_f32_e32 v220, v220, v84
	v_mul_f32_e32 v221, v221, v85
	v_mul_f32_e32 v222, v222, v86
	v_mul_f32_e32 v223, v223, v87
	v_mul_f32_e32 v224, v224, v88
	v_mul_f32_e32 v225, v225, v89
	v_mul_f32_e32 v226, v226, v90
	v_mul_f32_e32 v227, v227, v91
	v_mul_f32_e32 v228, v228, v92
	v_mul_f32_e32 v229, v229, v93
	v_mul_f32_e32 v230, v230, v94
	v_mul_f32_e32 v231, v231, v95
	s_mov_b32 s6, 0xffffffff
	s_mov_b32 s7, 0xfffffff0
	v_cndmask_b32_e64 v216, 0, v216, s[6:7]
	s_mov_b32 s6, 0xfffffffe
	s_mov_b32 s7, 0xffffffe0
	v_cndmask_b32_e64 v217, 0, v217, s[6:7]
	s_mov_b32 s6, 0xfffffffc
	s_mov_b32 s7, 0xffffffc0
	v_cndmask_b32_e64 v218, 0, v218, s[6:7]
	s_mov_b32 s6, 0xfffffff8
	s_mov_b32 s7, 0xffffff80
	v_cndmask_b32_e64 v219, 0, v219, s[6:7]
	s_mov_b32 s6, 0xffffff00
	s_mov_b32 s7, 0xfffff000
	v_cndmask_b32_e64 v220, 0, v220, s[6:7]
	s_mov_b32 s6, 0xfffffe00
	s_mov_b32 s7, 0xffffe000
	v_cndmask_b32_e64 v221, 0, v221, s[6:7]
	s_mov_b32 s6, 0xfffffc00
	s_mov_b32 s7, 0xffffc000
	v_cndmask_b32_e64 v222, 0, v222, s[6:7]
	s_mov_b32 s6, 0xfffff800
	s_mov_b32 s7, 0xffff8000
	v_cndmask_b32_e64 v223, 0, v223, s[6:7]
	s_mov_b32 s6, 0xffff0000
	s_mov_b32 s7, 0xfff00000
	v_cndmask_b32_e64 v224, 0, v224, s[6:7]
	s_mov_b32 s6, 0xfffe0000
	s_mov_b32 s7, 0xffe00000
	v_cndmask_b32_e64 v225, 0, v225, s[6:7]
	s_mov_b32 s6, 0xfffc0000
	s_mov_b32 s7, 0xffc00000
	v_cndmask_b32_e64 v226, 0, v226, s[6:7]
	s_mov_b32 s6, 0xfff80000
	s_mov_b32 s7, 0xff800000
	v_cndmask_b32_e64 v227, 0, v227, s[6:7]
	s_mov_b32 s6, 0xff000000
	s_mov_b32 s7, 0xf0000000
	v_cndmask_b32_e64 v228, 0, v228, s[6:7]
	s_mov_b32 s6, 0xfe000000
	s_mov_b32 s7, 0xe0000000
	v_cndmask_b32_e64 v229, 0, v229, s[6:7]
	s_mov_b32 s6, 0xfc000000
	s_mov_b32 s7, 0xc0000000
	v_cndmask_b32_e64 v230, 0, v230, s[6:7]
	s_mov_b32 s6, 0xf8000000
	s_mov_b32 s7, 0x80000000
	v_cndmask_b32_e64 v231, 0, v231, s[6:7]
	v_cvt_pk_bf16_f32 v80, v216, v217
	v_cvt_pk_bf16_f32 v81, v218, v219
	v_cvt_pk_bf16_f32 v82, v220, v221
	v_cvt_pk_bf16_f32 v83, v222, v223
	v_lshrrev_b32_e32 v112, 2, v152
	v_bitop3_b32 v114, v112, v196, 3 bitop3:0x6c
	v_mfma_f32_32x32x16_bf16 v[80:95], v[80:83], v[148:151], 0
	v_cvt_pk_bf16_f32 v148, v224, v225
	v_cvt_pk_bf16_f32 v149, v226, v227
	v_cvt_pk_bf16_f32 v150, v228, v229
	v_cvt_pk_bf16_f32 v151, v230, v231
	v_bitop3_b32 v104, v104, v112, 3 bitop3:0x78
	v_lshlrev_b32_e32 v102, 6, v197
	v_add_u32_e32 v106, s42, v102
	v_lshl_add_u32 v114, v114, 4, v106
	v_mfma_f32_32x32x16_bf16 v[80:95], v[148:151], v[140:143], v[80:95]
	ds_read_b128 v[140:143], v114 offset:16384
	ds_read_b128 v[148:151], v114 offset:18432
	v_exp_f32_e32 v100, v198
	v_lshl_add_u32 v104, v104, 4, v106
	v_pk_mul_f32 v[14:15], v[14:15], v[100:101] op_sel_hi:[1,0]
	v_pk_mul_f32 v[12:13], v[12:13], v[100:101] op_sel_hi:[1,0]
	v_pk_mul_f32 v[10:11], v[10:11], v[100:101] op_sel_hi:[1,0]
	v_pk_mul_f32 v[8:9], v[8:9], v[100:101] op_sel_hi:[1,0]
	v_pk_mul_f32 v[6:7], v[6:7], v[100:101] op_sel_hi:[1,0]
	v_pk_mul_f32 v[4:5], v[4:5], v[100:101] op_sel_hi:[1,0]
	v_pk_mul_f32 v[2:3], v[2:3], v[100:101] op_sel_hi:[1,0]
	v_pk_mul_f32 v[0:1], v[0:1], v[100:101] op_sel_hi:[1,0]
	v_pk_mul_f32 v[30:31], v[30:31], v[100:101] op_sel_hi:[1,0]
	v_pk_mul_f32 v[28:29], v[28:29], v[100:101] op_sel_hi:[1,0]
	s_waitcnt lgkmcnt(0)
	v_mfma_f32_32x32x16_bf16 v[0:15], v[140:143], v[108:111], v[0:15]
	ds_read_b128 v[140:143], v104 offset:16384
	ds_read_b128 v[196:199], v104 offset:18432
	v_mul_f32_e64 v26, v26, v100
	v_mul_f32_e64 v27, v27, v100
	v_mul_f32_e64 v24, v24, v100
	v_mul_f32_e64 v25, v25, v100
	v_pk_mul_f32 v[22:23], v[22:23], v[100:101] op_sel_hi:[1,0]
	v_pk_mul_f32 v[20:21], v[20:21], v[100:101] op_sel_hi:[1,0]
	v_pk_mul_f32 v[18:19], v[18:19], v[100:101] op_sel_hi:[1,0]
	v_pk_mul_f32 v[16:17], v[16:17], v[100:101] op_sel_hi:[1,0]
	s_waitcnt lgkmcnt(0)
	v_mfma_f32_32x32x16_bf16 v[0:15], v[140:143], v[96:99], v[0:15]
	ds_read_b128 v[140:143], v114 offset:20480
	v_mul_f32_e64 v46, v46, v100
	v_mul_f32_e64 v47, v47, v100
	v_mul_f32_e64 v44, v44, v100
	v_mul_f32_e64 v45, v45, v100
	v_pk_mul_f32 v[42:43], v[42:43], v[100:101] op_sel_hi:[1,0]
	v_pk_mul_f32 v[40:41], v[40:41], v[100:101] op_sel_hi:[1,0]
	v_pk_mul_f32 v[38:39], v[38:39], v[100:101] op_sel_hi:[1,0]
	v_pk_mul_f32 v[36:37], v[36:37], v[100:101] op_sel_hi:[1,0]
	v_mfma_f32_32x32x16_bf16 v[16:31], v[148:151], v[108:111], v[16:31]
	v_mul_f32_e64 v34, v34, v100
	v_mul_f32_e64 v35, v35, v100
	v_mul_f32_e64 v32, v32, v100
	v_mul_f32_e64 v33, v33, v100
	ds_read_b128 v[148:151], v114 offset:22528
	v_fma_f32 v64, v232, v64, v80
	v_fmac_f32_e32 v64, v159, v180
	v_pk_mul_f32 v[62:63], v[62:63], v[100:101] op_sel_hi:[1,0]
	v_pk_mul_f32 v[60:61], v[60:61], v[100:101] op_sel_hi:[1,0]
	v_mfma_f32_32x32x16_bf16 v[16:31], v[196:199], v[96:99], v[16:31]
	v_mul_f32_e64 v58, v58, v100
	v_mul_f32_e64 v59, v59, v100
	v_mul_f32_e64 v56, v56, v100
	v_mul_f32_e64 v57, v57, v100
	v_mul_f32_e64 v54, v54, v100
	v_mul_f32_e64 v55, v55, v100
	v_pk_mul_f32 v[52:53], v[52:53], v[100:101] op_sel_hi:[1,0]
	v_pk_mul_f32 v[50:51], v[50:51], v[100:101] op_sel_hi:[1,0]
	v_pk_mul_f32 v[48:49], v[48:49], v[100:101] op_sel_hi:[1,0]
	s_waitcnt lgkmcnt(0)
	v_mfma_f32_32x32x16_bf16 v[32:47], v[140:143], v[108:111], v[32:47]
	ds_read_b128 v[196:199], v104 offset:20480
	ds_read_b128 v[140:143], v104 offset:22528
	ds_read_u16 v104, v195 offset:40960
	ds_read_u16 v106, v195 offset:41024
	ds_read_u16 v112, v195 offset:41088
	ds_read_u16 v114, v195 offset:41152
	ds_read_u16 v116, v195 offset:41472
	ds_read_u16 v118, v195 offset:41536
	ds_read_u16 v120, v195 offset:41600
	ds_read_u16 v122, v195 offset:41664
	s_waitcnt lgkmcnt(0)
	v_lshlrev_b32_e32 v104, 16, v104
	v_mul_f32_e32 v124, 0xbfb8aa3b, v104
	v_exp_f32_e32 v124, v124
	s_nop 0
	v_add_f32_e32 v124, 1.0, v124
	v_rcp_f32_e32 v124, v124
	v_mfma_f32_32x32x16_bf16 v[48:63], v[148:151], v[108:111], v[48:63]
	v_mul_f32_e32 v80, v124, v104
	v_lshlrev_b32_e32 v104, 16, v106
	v_mul_f32_e32 v106, 0xbfb8aa3b, v104
	v_exp_f32_e32 v106, v106
	v_mul_f32_e32 v64, v64, v80
	v_cvt_pk_bf16_f32 v64, v64, s0
	v_add_f32_e32 v106, 1.0, v106
	ds_write_b16 v195, v64 offset:40960
	v_fma_f32 v64, v233, v65, v81
	v_lshlrev_b32_e32 v80, 16, v112
	v_rcp_f32_e32 v106, v106
	v_mul_f32_e32 v81, 0xbfb8aa3b, v80
	v_exp_f32_e32 v81, v81
	v_fmac_f32_e32 v64, v159, v181
	v_mul_f32_e32 v65, v106, v104
	v_mul_f32_e32 v64, v64, v65
	v_add_f32_e32 v81, 1.0, v81
	v_rcp_f32_e32 v81, v81
	v_cvt_pk_bf16_f32 v64, v64, s0
	ds_write_b16 v195, v64 offset:41024
	v_fma_f32 v64, v234, v66, v82
	v_lshlrev_b32_e32 v66, 16, v114
	v_mul_f32_e32 v65, v81, v80
	v_mul_f32_e32 v80, 0xbfb8aa3b, v66
	v_exp_f32_e32 v80, v80
	v_fmac_f32_e32 v64, v159, v178
	v_mul_f32_e32 v64, v64, v65
	v_add_f32_e32 v80, 1.0, v80
	v_rcp_f32_e32 v80, v80
	v_cvt_pk_bf16_f32 v64, v64, s0
	ds_write_b16 v195, v64 offset:41088
	v_fma_f32 v64, v235, v67, v83
	v_mul_f32_e32 v65, v80, v66
	v_lshlrev_b32_e32 v66, 16, v116
	v_mul_f32_e32 v67, 0xbfb8aa3b, v66
	v_exp_f32_e32 v67, v67
	v_fmac_f32_e32 v64, v159, v179
	v_mul_f32_e32 v64, v64, v65
	v_add_f32_e32 v67, 1.0, v67
	v_rcp_f32_e32 v67, v67
	v_cvt_pk_bf16_f32 v64, v64, s0
	ds_write_b16 v195, v64 offset:41152
	v_fma_f32 v64, v236, v68, v84
	v_mul_f32_e32 v65, v67, v66
	v_lshlrev_b32_e32 v66, 16, v118
	v_mul_f32_e32 v67, 0xbfb8aa3b, v66
	v_exp_f32_e32 v67, v67
	v_fmac_f32_e32 v64, v159, v176
	v_mul_f32_e32 v64, v64, v65
	v_add_f32_e32 v67, 1.0, v67
	v_rcp_f32_e32 v67, v67
	v_cvt_pk_bf16_f32 v64, v64, s0
	ds_write_b16 v195, v64 offset:41472
	v_fma_f32 v64, v237, v69, v85
	v_mul_f32_e32 v65, v67, v66
	v_lshlrev_b32_e32 v66, 16, v120
	v_mul_f32_e32 v67, 0xbfb8aa3b, v66
	v_exp_f32_e32 v67, v67
	v_fmac_f32_e32 v64, v159, v177
	v_mul_f32_e32 v64, v64, v65
	v_add_f32_e32 v67, 1.0, v67
	v_rcp_f32_e32 v67, v67
	v_cvt_pk_bf16_f32 v64, v64, s0
	ds_write_b16 v195, v64 offset:41536
	v_fma_f32 v64, v238, v70, v86
	v_mul_f32_e32 v65, v67, v66
	v_lshlrev_b32_e32 v66, 16, v122
	v_mul_f32_e32 v67, 0xbfb8aa3b, v66
	v_exp_f32_e32 v67, v67
	v_fmac_f32_e32 v64, v159, v174
	v_mul_f32_e32 v64, v64, v65
	v_add_f32_e32 v67, 1.0, v67
	v_rcp_f32_e32 v67, v67
	v_cvt_pk_bf16_f32 v64, v64, s0
	ds_write_b16 v195, v64 offset:41600
	v_fma_f32 v64, v239, v71, v87
	v_mul_f32_e32 v65, v67, v66
	ds_read_u16 v66, v195 offset:41984
	ds_read_u16 v67, v195 offset:42048
	ds_read_u16 v68, v195 offset:42112
	ds_read_u16 v69, v195 offset:42176
	ds_read_u16 v70, v195 offset:42496
	ds_read_u16 v71, v195 offset:42560
	ds_read_u16 v80, v195 offset:42624
	ds_read_u16 v81, v195 offset:42688
	s_waitcnt lgkmcnt(0)
	v_lshlrev_b32_e32 v66, 16, v66
	v_mul_f32_e32 v82, 0xbfb8aa3b, v66
	v_exp_f32_e32 v82, v82
	v_fmac_f32_e32 v64, v159, v175
	v_mul_f32_e32 v64, v64, v65
	v_add_f32_e32 v82, 1.0, v82
	v_rcp_f32_e32 v82, v82
	v_cvt_pk_bf16_f32 v64, v64, s0
	ds_write_b16 v195, v64 offset:41664
	v_fma_f32 v64, v240, v72, v88
	v_mul_f32_e32 v65, v82, v66
	v_lshlrev_b32_e32 v66, 16, v67
	v_mul_f32_e32 v67, 0xbfb8aa3b, v66
	v_exp_f32_e32 v67, v67
	v_fmac_f32_e32 v64, v159, v172
	v_mul_f32_e32 v64, v64, v65
	v_add_f32_e32 v67, 1.0, v67
	v_rcp_f32_e32 v67, v67
	v_cvt_pk_bf16_f32 v64, v64, s0
	ds_write_b16 v195, v64 offset:41984
	v_fma_f32 v64, v241, v73, v89
	v_mul_f32_e32 v65, v67, v66
	v_lshlrev_b32_e32 v66, 16, v68
	v_mul_f32_e32 v67, 0xbfb8aa3b, v66
	v_exp_f32_e32 v67, v67
	v_fmac_f32_e32 v64, v159, v173
	v_mul_f32_e32 v64, v64, v65
	v_add_f32_e32 v67, 1.0, v67
	v_rcp_f32_e32 v67, v67
	v_cvt_pk_bf16_f32 v64, v64, s0
	ds_write_b16 v195, v64 offset:42048
	v_fma_f32 v64, v242, v74, v90
	v_mul_f32_e32 v65, v67, v66
	v_lshlrev_b32_e32 v66, 16, v69
	v_mul_f32_e32 v67, 0xbfb8aa3b, v66
	v_exp_f32_e32 v67, v67
	v_fmac_f32_e32 v64, v159, v170
	v_mul_f32_e32 v64, v64, v65
	v_add_f32_e32 v67, 1.0, v67
	v_rcp_f32_e32 v67, v67
	v_cvt_pk_bf16_f32 v64, v64, s0
	ds_write_b16 v195, v64 offset:42112
	v_fma_f32 v64, v243, v75, v91
	v_mul_f32_e32 v65, v67, v66
	v_lshlrev_b32_e32 v66, 16, v70
	v_mul_f32_e32 v67, 0xbfb8aa3b, v66
	v_exp_f32_e32 v67, v67
	v_fmac_f32_e32 v64, v159, v171
	v_mul_f32_e32 v64, v64, v65
	v_add_f32_e32 v67, 1.0, v67
	v_rcp_f32_e32 v67, v67
	v_cvt_pk_bf16_f32 v64, v64, s0
	ds_write_b16 v195, v64 offset:42176
	v_fma_f32 v64, v244, v76, v92
	v_mul_f32_e32 v65, v67, v66
	v_lshlrev_b32_e32 v66, 16, v71
	v_mul_f32_e32 v67, 0xbfb8aa3b, v66
	v_exp_f32_e32 v67, v67
	v_fmac_f32_e32 v64, v159, v168
	v_mul_f32_e32 v64, v64, v65
	v_add_f32_e32 v67, 1.0, v67
	v_rcp_f32_e32 v67, v67
	v_cvt_pk_bf16_f32 v64, v64, s0
	ds_write_b16 v195, v64 offset:42496
	v_fma_f32 v64, v245, v77, v93
	v_mul_f32_e32 v65, v67, v66
	v_lshlrev_b32_e32 v66, 16, v80
	v_mul_f32_e32 v67, 0xbfb8aa3b, v66
	v_exp_f32_e32 v67, v67
	v_fmac_f32_e32 v64, v159, v169
	v_mul_f32_e32 v64, v64, v65
	v_add_f32_e32 v67, 1.0, v67
	v_rcp_f32_e32 v67, v67
	v_cvt_pk_bf16_f32 v64, v64, s0
	ds_write_b16 v195, v64 offset:42560
	v_fma_f32 v64, v246, v78, v94
	v_mul_f32_e32 v65, v67, v66
	v_lshlrev_b32_e32 v66, 16, v81
	v_mul_f32_e32 v67, 0xbfb8aa3b, v66
	v_exp_f32_e32 v67, v67
	v_fmac_f32_e32 v64, v159, v166
	v_mul_f32_e32 v64, v64, v65
	v_add_f32_e32 v67, 1.0, v67
	v_rcp_f32_e32 v67, v67
	v_cvt_pk_bf16_f32 v64, v64, s0
	v_fmac_f32_e32 v95, v247, v79
	ds_write_b16 v195, v64 offset:42624
	v_fmac_f32_e32 v95, v159, v167
	v_mul_f32_e32 v64, v67, v66
	v_mul_f32_e32 v64, v95, v64
	v_cvt_pk_bf16_f32 v64, v64, s0
	ds_write_b16 v195, v64 offset:42688
	s_waitcnt lgkmcnt(0)
	v_add3_u32 v68, s34, v102, v164
	ds_read_b128 v[64:67], v68 offset:40960
	ds_read_b128 v[68:71], v68 offset:40976
	v_mfma_f32_32x32x16_bf16 v[32:47], v[196:199], v[96:99], v[32:47]
	s_waitcnt lgkmcnt(0)
	v_lshlrev_b32_e32 v72, 16, v64
	v_and_b32_e32 v64, 0xffff0000, v64
	v_mul_f32_e32 v64, v64, v64
	v_lshlrev_b32_e32 v73, 16, v65
	v_fmac_f32_e32 v64, v72, v72
	v_and_b32_e32 v65, 0xffff0000, v65
	v_fmac_f32_e32 v64, v73, v73
	v_lshlrev_b32_e32 v74, 16, v66
	v_fmac_f32_e32 v64, v65, v65
	v_and_b32_e32 v66, 0xffff0000, v66
	v_fmac_f32_e32 v64, v74, v74
	v_lshlrev_b32_e32 v75, 16, v67
	v_fmac_f32_e32 v64, v66, v66
	v_and_b32_e32 v67, 0xffff0000, v67
	v_fmac_f32_e32 v64, v75, v75
	v_lshlrev_b32_e32 v76, 16, v68
	v_fmac_f32_e32 v64, v67, v67
	v_and_b32_e32 v68, 0xffff0000, v68
	v_fmac_f32_e32 v64, v76, v76
	v_lshlrev_b32_e32 v77, 16, v69
	v_fmac_f32_e32 v64, v68, v68
	v_and_b32_e32 v69, 0xffff0000, v69
	v_fmac_f32_e32 v64, v77, v77
	v_lshlrev_b32_e32 v78, 16, v70
	v_fmac_f32_e32 v64, v69, v69
	v_and_b32_e32 v70, 0xffff0000, v70
	v_fmac_f32_e32 v64, v78, v78
	v_lshlrev_b32_e32 v79, 16, v71
	v_fmac_f32_e32 v64, v70, v70
	v_mfma_f32_32x32x16_bf16 v[48:63], v[140:143], v[96:99], v[48:63]
	v_and_b32_e32 v71, 0xffff0000, v71
	v_fmac_f32_e32 v64, v79, v79
	v_fmac_f32_e32 v64, v71, v71
	ds_bpermute_b32 v65, v185, v64
	s_and_saveexec_b64 s[6:7], vcc
	s_cbranch_execz .LBB0_567
	s_waitcnt lgkmcnt(0)
	v_add_f32_e32 v66, v64, v65
	v_add_u32_e32 v64, s21, v152
	v_lshl_add_u32 v152, v64, 5, s93
	v_lshl_add_u64 v[64:65], v[152:153], 2, s[18:19]
	global_store_dword v[64:65], v66, off
	s_branch .LBB0_567
.LBB0_576:
	s_setprio 0
	v_mov_b32_e32 v64, v182
	s_add_i32 s6, s28, s94
	s_waitcnt lgkmcnt(0)
	v_lshrrev_b32_e32 v65, 2, v64
	v_lshl_add_u32 v72, v64, 4, s8
	v_lshlrev_b32_e32 v64, 3, v64
	v_add_u32_e32 v69, s6, v65
	v_and_or_b32 v68, v64, 24, s76
	ds_read_b128 v[64:67], v72 offset:40960
	v_mad_u64_u32 v[68:69], s[6:7], v69, s91, v[68:69]
	v_mov_b32_e32 v69, v153
	v_lshl_add_u64 v[70:71], v[68:69], 1, s[26:27]
	s_waitcnt lgkmcnt(0)
	global_store_dwordx4 v[70:71], v[64:67], off
	ds_read_b128 v[64:67], v72 offset:41984
	v_add_u32_e32 v152, 0x12000, v68
	v_lshl_add_u64 v[68:69], v[152:153], 1, s[26:27]
	s_waitcnt lgkmcnt(0)
	global_store_dwordx4 v[68:69], v[64:67], off
	s_waitcnt lgkmcnt(0)
	s_nop 1
	v_lshl_add_u64 v[64:65], s[44:45], 2, v[160:161]
	global_store_dwordx4 v[64:65], v[0:3], off
	global_store_dwordx4 v[64:65], v[4:7], off offset:32
	global_store_dwordx4 v[64:65], v[8:11], off offset:64
	global_store_dwordx4 v[64:65], v[12:15], off offset:96
	global_store_dwordx4 v[64:65], v[16:19], off offset:128
	global_store_dwordx4 v[64:65], v[20:23], off offset:160
	global_store_dwordx4 v[64:65], v[24:27], off offset:192
	global_store_dwordx4 v[64:65], v[28:31], off offset:224
	global_store_dwordx4 v[64:65], v[32:35], off offset:256
	global_store_dwordx4 v[64:65], v[36:39], off offset:288
	global_store_dwordx4 v[64:65], v[40:43], off offset:320
	global_store_dwordx4 v[64:65], v[44:47], off offset:352
	global_store_dwordx4 v[64:65], v[48:51], off offset:384
	global_store_dwordx4 v[64:65], v[52:55], off offset:416
	global_store_dwordx4 v[64:65], v[56:59], off offset:448
	global_store_dwordx4 v[64:65], v[60:63], off offset:480
	s_branch .LBB0_531
